# v24 plus evin GEMM: column-tile pair permuted so each workgroup's three units pair a heavy epilogue type (transposed V, ssq) with a light one (raw, rms)
# speedup vs baseline: 1.0010x; 1.0010x over previous
.LBB0_869:
	s_and_b64 vcc, exec, s[2:3]
	s_cbranch_vccz .LBB0_946
	v_readlane_b32 s4, v254, 48
	s_load_dwordx2 s[0:1], s[58:59], 0x98
	s_load_dwordx2 s[14:15], s[58:59], 0xe0
	v_readlane_b32 s5, v254, 49
	s_andn2_b64 vcc, exec, s[4:5]
	s_nop 0
	v_cndmask_b32_e64 v1, 0, 1, s[4:5]
	v_cmp_ne_u32_e64 s[6:7], 1, v1
	s_nop 1
	v_writelane_b32 v255, s6, 26
	s_nop 1
	v_writelane_b32 v255, s7, 27
	s_cbranch_vccnz .LBB0_947
	s_waitcnt lgkmcnt(0)
	s_add_u32 s2, s14, 0x9dd8800
	s_addc_u32 s3, s15, 0
	s_add_u32 s20, s14, 0x9ad8800
	s_addc_u32 s21, s15, 0
	s_add_u32 s22, s14, 0x9bd8800
	v_writelane_b32 v255, s2, 28
	s_addc_u32 s23, s15, 0
	s_load_dwordx2 s[16:17], s[58:59], 0x40
	v_writelane_b32 v255, s3, 29
	s_add_u32 s2, s14, 0x130e8800
	v_writelane_b32 v255, s2, 30
	s_addc_u32 s2, s15, 0
	v_writelane_b32 v255, s2, 32
	s_add_u32 s2, s14, 0x80
	v_writelane_b32 v255, s2, 33
	s_addc_u32 s2, s15, 0
	s_add_u32 s26, s14, 0x9dd8880
	s_addc_u32 s27, s15, 0
	s_add_u32 s93, s14, 0x148e8800
	s_addc_u32 s97, s15, 0
	v_writelane_b32 v255, s2, 34
	s_add_u32 s2, s14, 0x10dd8800
	v_writelane_b32 v255, s2, 35
	s_addc_u32 s2, s15, 0
	v_writelane_b32 v255, s2, 36
	s_add_u32 s2, s14, 0x105d8800
	v_writelane_b32 v255, s2, 37
	s_addc_u32 s2, s15, 0
	v_writelane_b32 v255, s2, 38
	s_add_u32 s2, s14, 0xfdd8800
	v_writelane_b32 v255, s2, 39
	s_addc_u32 s2, s15, 0
	v_writelane_b32 v255, s2, 40
	s_add_u32 s2, s14, 0x115d8800
	v_writelane_b32 v255, s2, 41
	s_addc_u32 s2, s15, 0
	v_writelane_b32 v255, s2, 42
	s_add_u32 s2, s14, 0x11dd8800
	v_writelane_b32 v255, s2, 43
	s_addc_u32 s2, s15, 0
	v_writelane_b32 v255, s2, 44
	s_add_u32 s2, s14, 0xddd8800
	v_writelane_b32 v255, s2, 45
	s_addc_u32 s2, s15, 0
	v_writelane_b32 v255, s2, 46
	v_readlane_b32 s58, v254, 8
	s_mov_b32 m0, s58
	s_branch .LBB0_873
.LBB0_872:
	v_readlane_b32 s94, v254, 11
	s_add_i32 m0, m0, s94
	v_readlane_b32 s76, v255, 15
	s_cmp_gt_i32 m0, 0x5ff
	v_readlane_b32 s49, v255, 14
	v_readlane_b32 s77, v255, 16
	v_readlane_b32 s57, v255, 17
	v_readlane_b32 s60, v255, 18
	v_readlane_b32 s66, v255, 19
	s_movk_i32 s68, 0x3fff
	s_mov_b32 s87, 0x1ffffc0
	s_movk_i32 s45, 0x70
	v_readlane_b32 s95, v254, 12
	s_cbranch_scc1 .LBB0_947
.LBB0_873:
	s_mul_hi_i32 s2, m0, 0x2aaaaaab
	s_lshr_b32 s3, s2, 31
	s_ashr_i32 s2, s2, 1
	s_add_i32 s2, s2, s3
	s_mul_i32 s3, s2, 12
	s_sub_i32 s3, m0, s3
	s_lshl_b32 s3, s3, 2
	s_mov_b32 s100, 0xba973210
	s_movk_i32 s101, 0x8654
	s_and_b32 s101, s101, 0xffff
	s_lshr_b64 s[100:101], s[100:101], s3
	s_and_b32 s3, s100, 15
	s_mul_i32 s58, s2, 12
	s_add_i32 s58, s58, s3
	s_mul_hi_i32 s2, s58, 0x2aaaaaab
	s_lshr_b32 s3, s2, 31
	s_ashr_i32 s42, s2, 1
	v_mov_b32_e32 v22, v208
	s_add_i32 s42, s42, s3
	s_lshl_b32 s28, s42, 7
	v_lshlrev_b32_e32 v3, 3, v22
	v_and_b32_e32 v1, 56, v3
	v_readlane_b32 s2, v255, 28
	v_ashrrev_i32_e32 v10, 3, v22
	v_lshlrev_b32_e32 v8, 1, v1
	v_mov_b32_e32 v9, v0
	v_readlane_b32 s3, v255, 29
	v_add_u32_e32 v2, s28, v10
	v_cmp_gt_u32_e64 s[6:7], s50, v2
	v_lshl_add_u64 v[16:17], s[2:3], 0, v[8:9]
	v_mov_b32_e32 v130, 0
	v_mov_b32_e32 v134, 0
	v_mov_b32_e32 v135, 0
	v_mov_b32_e32 v136, 0
	v_mov_b32_e32 v137, 0
	s_and_saveexec_b64 s[2:3], s[6:7]
	s_cbranch_execz .LBB0_875
	v_lshlrev_b32_e32 v4, 12, v2
	v_mov_b32_e32 v5, v0
	v_lshl_add_u64 v[4:5], v[16:17], 0, v[4:5]
	global_load_dwordx4 v[134:137], v[4:5], off
